# half-tile mode: LDS fragment reads of the unused A row half skipped too
# baseline (speedup 1.0000x reference)
.LBB0_253:
	s_add_i32 s82, s18, 2
	s_cmp_eq_u32 s70, s18
	s_cselect_b32 s18, s49, s78
	s_cselect_b32 s19, s47, s79
	s_cselect_b32 s56, s73, s80
	s_cselect_b32 s57, s72, s81
	s_add_u32 s26, s18, 0x80
	s_addc_u32 s27, s19, 0
	s_add_i32 s83, 0, 0x10000
	v_add_u32_e32 v0, s83, v213
	s_add_i32 s86, 0, 0x14000
	ds_read_b128 v[130:133], v0
	ds_read_b128 v[134:137], v0 offset:1024
	ds_read_b128 v[138:141], v0 offset:2048
	ds_read_b128 v[142:145], v0 offset:3072
	v_add_u32_e32 v0, s86, v213
	ds_read_b128 v[146:149], v0
	ds_read_b128 v[150:153], v0 offset:1024
	ds_read_b128 v[154:157], v0 offset:2048
	ds_read_b128 v[158:161], v0 offset:3072
	s_add_u32 s84, s78, 0x3ff80
	s_addc_u32 s85, s79, 0
	ds_read_b128 v[162:165], v216
	ds_read_b128 v[166:169], v216 offset:1024
	ds_read_b128 v[194:197], v216 offset:2048
	ds_read_b128 v[198:201], v216 offset:3072
	ds_read_b128 v[202:205], v216 offset:4096
	ds_read_b128 v[206:209], v216 offset:5120
	ds_read_b128 v[218:221], v216 offset:6144
	ds_read_b128 v[222:225], v216 offset:7168
	s_add_i32 m0, s40, 0xc000
	v_lshl_add_u64 v[210:211], s[84:85], 0, v[172:173]
	global_load_lds_dwordx4 v[210:211], off
	v_lshl_add_u64 v[210:211], s[84:85], 0, v[170:171]
	s_add_i32 m0, s40, 0xe000
	s_nop 0
	global_load_lds_dwordx4 v[210:211], off
	s_waitcnt vmcnt(8)
	s_waitcnt lgkmcnt(0)
	s_barrier
	s_setprio 1
	s_waitcnt lgkmcnt(0)
	v_mfma_f32_16x16x32_bf16 v[126:129], v[130:133], v[162:165], v[126:129]
	v_mfma_f32_16x16x32_bf16 v[122:125], v[138:141], v[162:165], v[122:125]
	v_mfma_f32_16x16x32_bf16 v[110:113], v[130:133], v[194:197], v[110:113]
	v_mfma_f32_16x16x32_bf16 v[106:109], v[138:141], v[194:197], v[106:109]
	v_mfma_f32_16x16x32_bf16 v[94:97], v[130:133], v[202:205], v[94:97]
	v_mfma_f32_16x16x32_bf16 v[90:93], v[138:141], v[202:205], v[90:93]
	v_mfma_f32_16x16x32_bf16 v[78:81], v[130:133], v[218:221], v[78:81]
	v_mfma_f32_16x16x32_bf16 v[74:77], v[138:141], v[218:221], v[74:77]
	v_mfma_f32_16x16x32_bf16 v[126:129], v[134:137], v[166:169], v[126:129]
	v_mfma_f32_16x16x32_bf16 v[122:125], v[142:145], v[166:169], v[122:125]
	v_mfma_f32_16x16x32_bf16 v[110:113], v[134:137], v[198:201], v[110:113]
	v_mfma_f32_16x16x32_bf16 v[106:109], v[142:145], v[198:201], v[106:109]
	v_mfma_f32_16x16x32_bf16 v[94:97], v[134:137], v[206:209], v[94:97]
	v_mfma_f32_16x16x32_bf16 v[90:93], v[142:145], v[206:209], v[90:93]
	v_mfma_f32_16x16x32_bf16 v[78:81], v[134:137], v[222:225], v[78:81]
	v_mfma_f32_16x16x32_bf16 v[74:77], v[142:145], v[222:225], v[74:77]
	v_mfma_f32_16x16x32_bf16 v[118:121], v[146:149], v[162:165], v[118:121]
	v_mfma_f32_16x16x32_bf16 v[114:117], v[154:157], v[162:165], v[114:117]
	v_mfma_f32_16x16x32_bf16 v[102:105], v[146:149], v[194:197], v[102:105]
	v_mfma_f32_16x16x32_bf16 v[98:101], v[154:157], v[194:197], v[98:101]
	v_mfma_f32_16x16x32_bf16 v[86:89], v[146:149], v[202:205], v[86:89]
	v_mfma_f32_16x16x32_bf16 v[82:85], v[154:157], v[202:205], v[82:85]
	v_mfma_f32_16x16x32_bf16 v[70:73], v[146:149], v[218:221], v[70:73]
	v_mfma_f32_16x16x32_bf16 v[66:69], v[154:157], v[218:221], v[66:69]
	v_mfma_f32_16x16x32_bf16 v[118:121], v[150:153], v[166:169], v[118:121]
	v_mfma_f32_16x16x32_bf16 v[114:117], v[158:161], v[166:169], v[114:117]
	v_mfma_f32_16x16x32_bf16 v[102:105], v[150:153], v[198:201], v[102:105]
	v_mfma_f32_16x16x32_bf16 v[98:101], v[158:161], v[198:201], v[98:101]
	v_mfma_f32_16x16x32_bf16 v[86:89], v[150:153], v[206:209], v[86:89]
	v_mfma_f32_16x16x32_bf16 v[82:85], v[158:161], v[206:209], v[82:85]
	v_mfma_f32_16x16x32_bf16 v[70:73], v[150:153], v[222:225], v[70:73]
	v_mfma_f32_16x16x32_bf16 v[66:69], v[158:161], v[222:225], v[66:69]
	s_setprio 0
	s_barrier
	s_mov_b64 s[84:85], s[56:57]
	s_add_i32 s83, s83, s25
	s_cmp_lg_u32 s100, 0
	s_cbranch_scc1 .Lh9_m0_r
	ds_read_b128 v[162:165], v216 offset:16384
	ds_read_b128 v[166:169], v216 offset:17408
	ds_read_b128 v[194:197], v216 offset:18432
	ds_read_b128 v[198:201], v216 offset:19456
	ds_read_b128 v[202:205], v216 offset:20480
	ds_read_b128 v[206:209], v216 offset:21504
	ds_read_b128 v[218:221], v216 offset:22528
	ds_read_b128 v[222:225], v216 offset:23552
.Lh9_m0_r:
	s_mov_b32 m0, s83
	v_lshl_add_u64 v[210:211], s[84:85], 0, v[172:173]
	global_load_lds_dwordx4 v[210:211], off
	s_add_i32 m0, s83, 0x2000
	v_lshl_add_u64 v[210:211], s[84:85], 0, v[170:171]
	s_add_u32 s84, s56, 0x40000
	s_addc_u32 s85, s57, 0
	s_add_i32 s83, s86, s25
	global_load_lds_dwordx4 v[210:211], off
	s_mov_b32 m0, s83
	v_lshl_add_u64 v[210:211], s[84:85], 0, v[172:173]
	global_load_lds_dwordx4 v[210:211], off
	v_lshl_add_u64 v[210:211], s[84:85], 0, v[170:171]
	s_add_i32 m0, s83, 0x2000
	s_mov_b64 s[84:85], s[18:19]
	global_load_lds_dwordx4 v[210:211], off
	s_mov_b32 m0, s40
	v_lshl_add_u64 v[210:211], s[84:85], 0, v[172:173]
	global_load_lds_dwordx4 v[210:211], off
	v_lshl_add_u64 v[210:211], s[84:85], 0, v[170:171]
	s_mov_b32 m0, s41
	s_nop 0
	global_load_lds_dwordx4 v[210:211], off
	s_waitcnt vmcnt(8)
	s_waitcnt lgkmcnt(0)
	s_barrier
	s_setprio 1
	s_waitcnt lgkmcnt(0)
	s_cmp_lg_u32 s100, 0
	s_cbranch_scc1 .Lh9_m0
	v_mfma_f32_16x16x32_bf16 v[62:65], v[130:133], v[162:165], v[62:65]
	v_mfma_f32_16x16x32_bf16 v[58:61], v[138:141], v[162:165], v[58:61]
	v_mfma_f32_16x16x32_bf16 v[46:49], v[130:133], v[194:197], v[46:49]
	v_mfma_f32_16x16x32_bf16 v[42:45], v[138:141], v[194:197], v[42:45]
	v_mfma_f32_16x16x32_bf16 v[30:33], v[130:133], v[202:205], v[30:33]
	v_mfma_f32_16x16x32_bf16 v[26:29], v[138:141], v[202:205], v[26:29]
	v_mfma_f32_16x16x32_bf16 v[14:17], v[130:133], v[218:221], v[14:17]
	v_mfma_f32_16x16x32_bf16 v[10:13], v[138:141], v[218:221], v[10:13]
	v_mfma_f32_16x16x32_bf16 v[62:65], v[134:137], v[166:169], v[62:65]
	v_mfma_f32_16x16x32_bf16 v[58:61], v[142:145], v[166:169], v[58:61]
	v_mfma_f32_16x16x32_bf16 v[46:49], v[134:137], v[198:201], v[46:49]
	v_mfma_f32_16x16x32_bf16 v[42:45], v[142:145], v[198:201], v[42:45]
	v_mfma_f32_16x16x32_bf16 v[30:33], v[134:137], v[206:209], v[30:33]
	v_mfma_f32_16x16x32_bf16 v[26:29], v[142:145], v[206:209], v[26:29]
	v_mfma_f32_16x16x32_bf16 v[14:17], v[134:137], v[222:225], v[14:17]
	v_mfma_f32_16x16x32_bf16 v[10:13], v[142:145], v[222:225], v[10:13]
	v_mfma_f32_16x16x32_bf16 v[54:57], v[146:149], v[162:165], v[54:57]
	v_mfma_f32_16x16x32_bf16 v[50:53], v[154:157], v[162:165], v[50:53]
	v_mfma_f32_16x16x32_bf16 v[38:41], v[146:149], v[194:197], v[38:41]
	v_mfma_f32_16x16x32_bf16 v[34:37], v[154:157], v[194:197], v[34:37]
	v_mfma_f32_16x16x32_bf16 v[22:25], v[146:149], v[202:205], v[22:25]
	v_mfma_f32_16x16x32_bf16 v[18:21], v[154:157], v[202:205], v[18:21]
	v_mfma_f32_16x16x32_bf16 v[6:9], v[146:149], v[218:221], v[6:9]
	v_mfma_f32_16x16x32_bf16 v[2:5], v[154:157], v[218:221], v[2:5]
	v_mfma_f32_16x16x32_bf16 v[54:57], v[150:153], v[166:169], v[54:57]
	v_mfma_f32_16x16x32_bf16 v[50:53], v[158:161], v[166:169], v[50:53]
	v_mfma_f32_16x16x32_bf16 v[38:41], v[150:153], v[198:201], v[38:41]
	v_mfma_f32_16x16x32_bf16 v[34:37], v[158:161], v[198:201], v[34:37]
	v_mfma_f32_16x16x32_bf16 v[22:25], v[150:153], v[206:209], v[22:25]
	v_mfma_f32_16x16x32_bf16 v[18:21], v[158:161], v[206:209], v[18:21]
	v_mfma_f32_16x16x32_bf16 v[6:9], v[150:153], v[222:225], v[6:9]
	v_mfma_f32_16x16x32_bf16 v[2:5], v[158:161], v[222:225], v[2:5]
.Lh9_m0:
	s_setprio 0
	s_barrier
	s_add_i32 s83, 0, 0x18000
	v_add_u32_e32 v0, s83, v213
	s_add_i32 s84, 0, 0x1c000
	ds_read_b128 v[130:133], v0
	ds_read_b128 v[134:137], v0 offset:1024
	ds_read_b128 v[138:141], v0 offset:2048
	ds_read_b128 v[142:145], v0 offset:3072
	v_add_u32_e32 v0, s84, v213
	ds_read_b128 v[146:149], v0
	ds_read_b128 v[150:153], v0 offset:1024
	ds_read_b128 v[154:157], v0 offset:2048
	ds_read_b128 v[158:161], v0 offset:3072
	s_add_u32 s18, s18, 0x40000
	s_addc_u32 s19, s19, 0
	s_mov_b32 m0, s60
	ds_read_b128 v[162:165], v216 offset:32768
	ds_read_b128 v[166:169], v216 offset:33792
	ds_read_b128 v[194:197], v216 offset:34816
	ds_read_b128 v[198:201], v216 offset:35840
	ds_read_b128 v[202:205], v216 offset:36864
	ds_read_b128 v[206:209], v216 offset:37888
	ds_read_b128 v[218:221], v216 offset:38912
	ds_read_b128 v[222:225], v216 offset:39936
	s_nop 0
	v_lshl_add_u64 v[210:211], s[18:19], 0, v[172:173]
	global_load_lds_dwordx4 v[210:211], off
	v_lshl_add_u64 v[210:211], s[18:19], 0, v[170:171]
	s_mov_b32 m0, s61
	s_nop 0
	global_load_lds_dwordx4 v[210:211], off
	s_waitcnt vmcnt(8)
	s_waitcnt lgkmcnt(0)
	s_barrier
	s_setprio 1
	s_waitcnt lgkmcnt(0)
	v_mfma_f32_16x16x32_bf16 v[126:129], v[130:133], v[162:165], v[126:129]
	v_mfma_f32_16x16x32_bf16 v[122:125], v[138:141], v[162:165], v[122:125]
	v_mfma_f32_16x16x32_bf16 v[110:113], v[130:133], v[194:197], v[110:113]
	v_mfma_f32_16x16x32_bf16 v[106:109], v[138:141], v[194:197], v[106:109]
	v_mfma_f32_16x16x32_bf16 v[94:97], v[130:133], v[202:205], v[94:97]
	v_mfma_f32_16x16x32_bf16 v[90:93], v[138:141], v[202:205], v[90:93]
	v_mfma_f32_16x16x32_bf16 v[78:81], v[130:133], v[218:221], v[78:81]
	v_mfma_f32_16x16x32_bf16 v[74:77], v[138:141], v[218:221], v[74:77]
	v_mfma_f32_16x16x32_bf16 v[126:129], v[134:137], v[166:169], v[126:129]
	v_mfma_f32_16x16x32_bf16 v[122:125], v[142:145], v[166:169], v[122:125]
	v_mfma_f32_16x16x32_bf16 v[110:113], v[134:137], v[198:201], v[110:113]
	v_mfma_f32_16x16x32_bf16 v[106:109], v[142:145], v[198:201], v[106:109]
	v_mfma_f32_16x16x32_bf16 v[94:97], v[134:137], v[206:209], v[94:97]
	v_mfma_f32_16x16x32_bf16 v[90:93], v[142:145], v[206:209], v[90:93]
	v_mfma_f32_16x16x32_bf16 v[78:81], v[134:137], v[222:225], v[78:81]
	v_mfma_f32_16x16x32_bf16 v[74:77], v[142:145], v[222:225], v[74:77]
	v_mfma_f32_16x16x32_bf16 v[118:121], v[146:149], v[162:165], v[118:121]
	v_mfma_f32_16x16x32_bf16 v[114:117], v[154:157], v[162:165], v[114:117]
	v_mfma_f32_16x16x32_bf16 v[102:105], v[146:149], v[194:197], v[102:105]
	v_mfma_f32_16x16x32_bf16 v[98:101], v[154:157], v[194:197], v[98:101]
	v_mfma_f32_16x16x32_bf16 v[86:89], v[146:149], v[202:205], v[86:89]
	v_mfma_f32_16x16x32_bf16 v[82:85], v[154:157], v[202:205], v[82:85]
	v_mfma_f32_16x16x32_bf16 v[70:73], v[146:149], v[218:221], v[70:73]
	v_mfma_f32_16x16x32_bf16 v[66:69], v[154:157], v[218:221], v[66:69]
	v_mfma_f32_16x16x32_bf16 v[118:121], v[150:153], v[166:169], v[118:121]
	v_mfma_f32_16x16x32_bf16 v[114:117], v[158:161], v[166:169], v[114:117]
	v_mfma_f32_16x16x32_bf16 v[102:105], v[150:153], v[198:201], v[102:105]
	v_mfma_f32_16x16x32_bf16 v[98:101], v[158:161], v[198:201], v[98:101]
	v_mfma_f32_16x16x32_bf16 v[86:89], v[150:153], v[206:209], v[86:89]
	v_mfma_f32_16x16x32_bf16 v[82:85], v[158:161], v[206:209], v[82:85]
	v_mfma_f32_16x16x32_bf16 v[70:73], v[150:153], v[222:225], v[70:73]
	v_mfma_f32_16x16x32_bf16 v[66:69], v[158:161], v[222:225], v[66:69]
	s_setprio 0
	s_barrier
	s_add_u32 s18, s56, 0x80
	s_addc_u32 s19, s57, 0
	s_add_i32 s83, s83, s25
	s_cmp_lg_u32 s100, 0
	s_cbranch_scc1 .Lh9_m1_r
	ds_read_b128 v[162:165], v216 offset:49152
	ds_read_b128 v[166:169], v216 offset:50176
	ds_read_b128 v[194:197], v216 offset:51200
	ds_read_b128 v[198:201], v216 offset:52224
	ds_read_b128 v[202:205], v216 offset:53248
	ds_read_b128 v[206:209], v216 offset:54272
	ds_read_b128 v[218:221], v216 offset:55296
	ds_read_b128 v[222:225], v216 offset:56320
.Lh9_m1_r:
	s_mov_b32 m0, s83
	v_lshl_add_u64 v[210:211], s[18:19], 0, v[172:173]
	global_load_lds_dwordx4 v[210:211], off
	s_add_i32 m0, s83, 0x2000
	v_lshl_add_u64 v[210:211], s[18:19], 0, v[170:171]
	s_add_u32 s18, s56, 0x40080
	s_addc_u32 s19, s57, 0
	s_add_i32 s56, s84, s25
	global_load_lds_dwordx4 v[210:211], off
	s_mov_b32 m0, s56
	v_lshl_add_u64 v[210:211], s[18:19], 0, v[172:173]
	global_load_lds_dwordx4 v[210:211], off
	v_lshl_add_u64 v[210:211], s[18:19], 0, v[170:171]
	s_add_i32 m0, s56, 0x2000
	s_nop 0
	global_load_lds_dwordx4 v[210:211], off
	s_mov_b32 m0, s68
	v_lshl_add_u64 v[210:211], s[26:27], 0, v[172:173]
	global_load_lds_dwordx4 v[210:211], off
	v_lshl_add_u64 v[210:211], s[26:27], 0, v[170:171]
	s_mov_b32 m0, s69
	s_nop 0
	global_load_lds_dwordx4 v[210:211], off
	s_waitcnt vmcnt(8)
	s_waitcnt lgkmcnt(0)
	s_barrier
	s_setprio 1
	s_waitcnt lgkmcnt(0)
	s_cmp_lg_u32 s100, 0
	s_cbranch_scc1 .Lh9_m1
	v_mfma_f32_16x16x32_bf16 v[62:65], v[130:133], v[162:165], v[62:65]
	v_mfma_f32_16x16x32_bf16 v[58:61], v[138:141], v[162:165], v[58:61]
	v_mfma_f32_16x16x32_bf16 v[46:49], v[130:133], v[194:197], v[46:49]
	v_mfma_f32_16x16x32_bf16 v[42:45], v[138:141], v[194:197], v[42:45]
	v_mfma_f32_16x16x32_bf16 v[30:33], v[130:133], v[202:205], v[30:33]
	v_mfma_f32_16x16x32_bf16 v[26:29], v[138:141], v[202:205], v[26:29]
	v_mfma_f32_16x16x32_bf16 v[14:17], v[130:133], v[218:221], v[14:17]
	v_mfma_f32_16x16x32_bf16 v[10:13], v[138:141], v[218:221], v[10:13]
	v_mfma_f32_16x16x32_bf16 v[62:65], v[134:137], v[166:169], v[62:65]
	v_mfma_f32_16x16x32_bf16 v[58:61], v[142:145], v[166:169], v[58:61]
	v_mfma_f32_16x16x32_bf16 v[46:49], v[134:137], v[198:201], v[46:49]
	v_mfma_f32_16x16x32_bf16 v[42:45], v[142:145], v[198:201], v[42:45]
	v_mfma_f32_16x16x32_bf16 v[30:33], v[134:137], v[206:209], v[30:33]
	v_mfma_f32_16x16x32_bf16 v[26:29], v[142:145], v[206:209], v[26:29]
	v_mfma_f32_16x16x32_bf16 v[14:17], v[134:137], v[222:225], v[14:17]
	v_mfma_f32_16x16x32_bf16 v[10:13], v[142:145], v[222:225], v[10:13]
	v_mfma_f32_16x16x32_bf16 v[54:57], v[146:149], v[162:165], v[54:57]
	v_mfma_f32_16x16x32_bf16 v[50:53], v[154:157], v[162:165], v[50:53]
	v_mfma_f32_16x16x32_bf16 v[38:41], v[146:149], v[194:197], v[38:41]
	v_mfma_f32_16x16x32_bf16 v[34:37], v[154:157], v[194:197], v[34:37]
	v_mfma_f32_16x16x32_bf16 v[22:25], v[146:149], v[202:205], v[22:25]
	v_mfma_f32_16x16x32_bf16 v[18:21], v[154:157], v[202:205], v[18:21]
	v_mfma_f32_16x16x32_bf16 v[6:9], v[146:149], v[218:221], v[6:9]
	v_mfma_f32_16x16x32_bf16 v[2:5], v[154:157], v[218:221], v[2:5]
	v_mfma_f32_16x16x32_bf16 v[54:57], v[150:153], v[166:169], v[54:57]
	v_mfma_f32_16x16x32_bf16 v[50:53], v[158:161], v[166:169], v[50:53]
	v_mfma_f32_16x16x32_bf16 v[38:41], v[150:153], v[198:201], v[38:41]
	v_mfma_f32_16x16x32_bf16 v[34:37], v[158:161], v[198:201], v[34:37]
	v_mfma_f32_16x16x32_bf16 v[22:25], v[150:153], v[206:209], v[22:25]
	v_mfma_f32_16x16x32_bf16 v[18:21], v[158:161], v[206:209], v[18:21]
	v_mfma_f32_16x16x32_bf16 v[6:9], v[150:153], v[222:225], v[6:9]
	v_mfma_f32_16x16x32_bf16 v[2:5], v[158:161], v[222:225], v[2:5]

.LBB0_691:
	s_add_i32 s92, s18, 2
	s_cmp_eq_u32 s84, s18
	s_cselect_b32 s18, s37, vcc_lo
	s_cselect_b32 s19, s1, vcc_hi
	s_cselect_b32 s72, s89, s90
	s_cselect_b32 s73, s57, s91
	s_add_u32 s26, s18, 0x80
	s_addc_u32 s27, s19, 0
	s_add_i32 s93, 0, 0x10000
	v_add_u32_e32 v0, s93, v222
	s_add_i32 s96, 0, 0x14000
	ds_read_b128 v[66:69], v0
	ds_read_b128 v[70:73], v0 offset:1024
	ds_read_b128 v[74:77], v0 offset:2048
	ds_read_b128 v[78:81], v0 offset:3072
	v_add_u32_e32 v0, s96, v222
	ds_read_b128 v[146:149], v0
	ds_read_b128 v[150:153], v0 offset:1024
	ds_read_b128 v[154:157], v0 offset:2048
	ds_read_b128 v[158:161], v0 offset:3072
	s_mov_b64 s[94:95], s[2:3]
	ds_read_b128 v[162:165], v223
	ds_read_b128 v[166:169], v223 offset:1024
	ds_read_b128 v[198:201], v223 offset:2048
	ds_read_b128 v[202:205], v223 offset:3072
	ds_read_b128 v[206:209], v223 offset:4096
	ds_read_b128 v[210:213], v223 offset:5120
	ds_read_b128 v[214:217], v223 offset:6144
	ds_read_b128 v[218:221], v223 offset:7168
	s_add_i32 m0, s67, 0xc000
	v_lshl_add_u64 v[224:225], s[94:95], 0, v[196:197]
	global_load_lds_dwordx4 v[224:225], off
	v_lshl_add_u64 v[224:225], s[94:95], 0, v[172:173]
	s_add_i32 m0, s67, 0xe000
	s_nop 0
	global_load_lds_dwordx4 v[224:225], off
	s_waitcnt vmcnt(8)
	s_waitcnt lgkmcnt(0)
	s_barrier
	s_setprio 1
	s_waitcnt lgkmcnt(0)
	v_mfma_f32_16x16x32_bf16 v[138:141], v[66:69], v[162:165], v[138:141]
	v_mfma_f32_16x16x32_bf16 v[142:145], v[74:77], v[162:165], v[142:145]
	v_mfma_f32_16x16x32_bf16 v[126:129], v[66:69], v[198:201], v[126:129]
	v_mfma_f32_16x16x32_bf16 v[122:125], v[74:77], v[198:201], v[122:125]
	v_mfma_f32_16x16x32_bf16 v[110:113], v[66:69], v[206:209], v[110:113]
	v_mfma_f32_16x16x32_bf16 v[106:109], v[74:77], v[206:209], v[106:109]
	v_mfma_f32_16x16x32_bf16 v[94:97], v[66:69], v[214:217], v[94:97]
	v_mfma_f32_16x16x32_bf16 v[90:93], v[74:77], v[214:217], v[90:93]
	v_mfma_f32_16x16x32_bf16 v[138:141], v[70:73], v[166:169], v[138:141]
	v_mfma_f32_16x16x32_bf16 v[142:145], v[78:81], v[166:169], v[142:145]
	v_mfma_f32_16x16x32_bf16 v[126:129], v[70:73], v[202:205], v[126:129]
	v_mfma_f32_16x16x32_bf16 v[122:125], v[78:81], v[202:205], v[122:125]
	v_mfma_f32_16x16x32_bf16 v[110:113], v[70:73], v[210:213], v[110:113]
	v_mfma_f32_16x16x32_bf16 v[106:109], v[78:81], v[210:213], v[106:109]
	v_mfma_f32_16x16x32_bf16 v[94:97], v[70:73], v[218:221], v[94:97]
	v_mfma_f32_16x16x32_bf16 v[90:93], v[78:81], v[218:221], v[90:93]
	v_mfma_f32_16x16x32_bf16 v[134:137], v[146:149], v[162:165], v[134:137]
	v_mfma_f32_16x16x32_bf16 v[130:133], v[154:157], v[162:165], v[130:133]
	v_mfma_f32_16x16x32_bf16 v[118:121], v[146:149], v[198:201], v[118:121]
	v_mfma_f32_16x16x32_bf16 v[114:117], v[154:157], v[198:201], v[114:117]
	v_mfma_f32_16x16x32_bf16 v[102:105], v[146:149], v[206:209], v[102:105]
	v_mfma_f32_16x16x32_bf16 v[98:101], v[154:157], v[206:209], v[98:101]
	v_mfma_f32_16x16x32_bf16 v[86:89], v[146:149], v[214:217], v[86:89]
	v_mfma_f32_16x16x32_bf16 v[82:85], v[154:157], v[214:217], v[82:85]
	v_mfma_f32_16x16x32_bf16 v[134:137], v[150:153], v[166:169], v[134:137]
	v_mfma_f32_16x16x32_bf16 v[130:133], v[158:161], v[166:169], v[130:133]
	v_mfma_f32_16x16x32_bf16 v[118:121], v[150:153], v[202:205], v[118:121]
	v_mfma_f32_16x16x32_bf16 v[114:117], v[158:161], v[202:205], v[114:117]
	v_mfma_f32_16x16x32_bf16 v[102:105], v[150:153], v[210:213], v[102:105]
	v_mfma_f32_16x16x32_bf16 v[98:101], v[158:161], v[210:213], v[98:101]
	v_mfma_f32_16x16x32_bf16 v[86:89], v[150:153], v[218:221], v[86:89]
	v_mfma_f32_16x16x32_bf16 v[82:85], v[158:161], v[218:221], v[82:85]
	s_setprio 0
	s_barrier
	s_mov_b64 s[94:95], s[72:73]
	s_add_i32 s93, s93, s25
	s_cmp_lg_u32 s100, 0
	s_cbranch_scc1 .Lh13_m0_r
	ds_read_b128 v[162:165], v223 offset:16384
	ds_read_b128 v[166:169], v223 offset:17408
	ds_read_b128 v[198:201], v223 offset:18432
	ds_read_b128 v[202:205], v223 offset:19456
	ds_read_b128 v[206:209], v223 offset:20480
	ds_read_b128 v[210:213], v223 offset:21504
	ds_read_b128 v[214:217], v223 offset:22528
	ds_read_b128 v[218:221], v223 offset:23552
.Lh13_m0_r:
	s_mov_b32 m0, s93
	v_lshl_add_u64 v[224:225], s[94:95], 0, v[194:195]
	global_load_lds_dwordx4 v[224:225], off
	s_add_i32 m0, s93, 0x2000
	v_lshl_add_u64 v[224:225], s[94:95], 0, v[170:171]
	s_add_u32 s94, s72, 0x40000
	s_addc_u32 s95, s73, 0
	s_add_i32 s93, s96, s25
	global_load_lds_dwordx4 v[224:225], off
	s_mov_b32 m0, s93
	v_lshl_add_u64 v[224:225], s[94:95], 0, v[194:195]
	global_load_lds_dwordx4 v[224:225], off
	v_lshl_add_u64 v[224:225], s[94:95], 0, v[170:171]
	s_add_i32 m0, s93, 0x2000
	s_mov_b64 s[94:95], s[18:19]
	global_load_lds_dwordx4 v[224:225], off
	s_mov_b32 m0, s67
	v_lshl_add_u64 v[224:225], s[94:95], 0, v[196:197]
	global_load_lds_dwordx4 v[224:225], off
	v_lshl_add_u64 v[224:225], s[94:95], 0, v[172:173]
	s_mov_b32 m0, s68
	s_nop 0
	global_load_lds_dwordx4 v[224:225], off
	s_waitcnt vmcnt(8)
	s_waitcnt lgkmcnt(0)
	s_barrier
	s_setprio 1
	s_waitcnt lgkmcnt(0)
	s_cmp_lg_u32 s100, 0
	s_cbranch_scc1 .Lh13_m0
	v_mfma_f32_16x16x32_bf16 v[62:65], v[66:69], v[162:165], v[62:65]
	v_mfma_f32_16x16x32_bf16 v[58:61], v[74:77], v[162:165], v[58:61]
	v_mfma_f32_16x16x32_bf16 v[46:49], v[66:69], v[198:201], v[46:49]
	v_mfma_f32_16x16x32_bf16 v[42:45], v[74:77], v[198:201], v[42:45]
	v_mfma_f32_16x16x32_bf16 v[30:33], v[66:69], v[206:209], v[30:33]
	v_mfma_f32_16x16x32_bf16 v[26:29], v[74:77], v[206:209], v[26:29]
	v_mfma_f32_16x16x32_bf16 v[14:17], v[66:69], v[214:217], v[14:17]
	v_mfma_f32_16x16x32_bf16 v[10:13], v[74:77], v[214:217], v[10:13]
	v_mfma_f32_16x16x32_bf16 v[62:65], v[70:73], v[166:169], v[62:65]
	v_mfma_f32_16x16x32_bf16 v[58:61], v[78:81], v[166:169], v[58:61]
	v_mfma_f32_16x16x32_bf16 v[46:49], v[70:73], v[202:205], v[46:49]
	v_mfma_f32_16x16x32_bf16 v[42:45], v[78:81], v[202:205], v[42:45]
	v_mfma_f32_16x16x32_bf16 v[30:33], v[70:73], v[210:213], v[30:33]
	v_mfma_f32_16x16x32_bf16 v[26:29], v[78:81], v[210:213], v[26:29]
	v_mfma_f32_16x16x32_bf16 v[14:17], v[70:73], v[218:221], v[14:17]
	v_mfma_f32_16x16x32_bf16 v[10:13], v[78:81], v[218:221], v[10:13]
	v_mfma_f32_16x16x32_bf16 v[54:57], v[146:149], v[162:165], v[54:57]
	v_mfma_f32_16x16x32_bf16 v[50:53], v[154:157], v[162:165], v[50:53]
	v_mfma_f32_16x16x32_bf16 v[38:41], v[146:149], v[198:201], v[38:41]
	v_mfma_f32_16x16x32_bf16 v[34:37], v[154:157], v[198:201], v[34:37]
	v_mfma_f32_16x16x32_bf16 v[22:25], v[146:149], v[206:209], v[22:25]
	v_mfma_f32_16x16x32_bf16 v[18:21], v[154:157], v[206:209], v[18:21]
	v_mfma_f32_16x16x32_bf16 v[6:9], v[146:149], v[214:217], v[6:9]
	v_mfma_f32_16x16x32_bf16 v[2:5], v[154:157], v[214:217], v[2:5]
	v_mfma_f32_16x16x32_bf16 v[54:57], v[150:153], v[166:169], v[54:57]
	v_mfma_f32_16x16x32_bf16 v[50:53], v[158:161], v[166:169], v[50:53]
	v_mfma_f32_16x16x32_bf16 v[38:41], v[150:153], v[202:205], v[38:41]
	v_mfma_f32_16x16x32_bf16 v[34:37], v[158:161], v[202:205], v[34:37]
	v_mfma_f32_16x16x32_bf16 v[22:25], v[150:153], v[210:213], v[22:25]
	v_mfma_f32_16x16x32_bf16 v[18:21], v[158:161], v[210:213], v[18:21]
	v_mfma_f32_16x16x32_bf16 v[6:9], v[150:153], v[218:221], v[6:9]
	v_mfma_f32_16x16x32_bf16 v[2:5], v[158:161], v[218:221], v[2:5]
.Lh13_m0:
	s_setprio 0
	s_barrier
	s_add_i32 s93, 0, 0x18000
	v_add_u32_e32 v0, s93, v222
	s_add_i32 s94, 0, 0x1c000
	ds_read_b128 v[66:69], v0
	ds_read_b128 v[70:73], v0 offset:1024
	ds_read_b128 v[74:77], v0 offset:2048
	ds_read_b128 v[78:81], v0 offset:3072
	v_add_u32_e32 v0, s94, v222
	ds_read_b128 v[146:149], v0
	ds_read_b128 v[150:153], v0 offset:1024
	ds_read_b128 v[154:157], v0 offset:2048
	ds_read_b128 v[158:161], v0 offset:3072
	s_add_u32 s18, s18, 0x40000
	s_addc_u32 s19, s19, 0
	s_mov_b32 m0, s69
	ds_read_b128 v[162:165], v223 offset:32768
	ds_read_b128 v[166:169], v223 offset:33792
	ds_read_b128 v[198:201], v223 offset:34816
	ds_read_b128 v[202:205], v223 offset:35840
	ds_read_b128 v[206:209], v223 offset:36864
	ds_read_b128 v[210:213], v223 offset:37888
	ds_read_b128 v[214:217], v223 offset:38912
	ds_read_b128 v[218:221], v223 offset:39936
	s_nop 0
	v_lshl_add_u64 v[224:225], s[18:19], 0, v[196:197]
	global_load_lds_dwordx4 v[224:225], off
	v_lshl_add_u64 v[224:225], s[18:19], 0, v[172:173]
	s_mov_b32 m0, s70
	s_nop 0
	global_load_lds_dwordx4 v[224:225], off
	s_waitcnt vmcnt(8)
	s_waitcnt lgkmcnt(0)
	s_barrier
	s_setprio 1
	s_waitcnt lgkmcnt(0)
	v_mfma_f32_16x16x32_bf16 v[138:141], v[66:69], v[162:165], v[138:141]
	v_mfma_f32_16x16x32_bf16 v[142:145], v[74:77], v[162:165], v[142:145]
	v_mfma_f32_16x16x32_bf16 v[126:129], v[66:69], v[198:201], v[126:129]
	v_mfma_f32_16x16x32_bf16 v[122:125], v[74:77], v[198:201], v[122:125]
	v_mfma_f32_16x16x32_bf16 v[110:113], v[66:69], v[206:209], v[110:113]
	v_mfma_f32_16x16x32_bf16 v[106:109], v[74:77], v[206:209], v[106:109]
	v_mfma_f32_16x16x32_bf16 v[94:97], v[66:69], v[214:217], v[94:97]
	v_mfma_f32_16x16x32_bf16 v[90:93], v[74:77], v[214:217], v[90:93]
	v_mfma_f32_16x16x32_bf16 v[138:141], v[70:73], v[166:169], v[138:141]
	v_mfma_f32_16x16x32_bf16 v[142:145], v[78:81], v[166:169], v[142:145]
	v_mfma_f32_16x16x32_bf16 v[126:129], v[70:73], v[202:205], v[126:129]
	v_mfma_f32_16x16x32_bf16 v[122:125], v[78:81], v[202:205], v[122:125]
	v_mfma_f32_16x16x32_bf16 v[110:113], v[70:73], v[210:213], v[110:113]
	v_mfma_f32_16x16x32_bf16 v[106:109], v[78:81], v[210:213], v[106:109]
	v_mfma_f32_16x16x32_bf16 v[94:97], v[70:73], v[218:221], v[94:97]
	v_mfma_f32_16x16x32_bf16 v[90:93], v[78:81], v[218:221], v[90:93]
	v_mfma_f32_16x16x32_bf16 v[134:137], v[146:149], v[162:165], v[134:137]
	v_mfma_f32_16x16x32_bf16 v[130:133], v[154:157], v[162:165], v[130:133]
	v_mfma_f32_16x16x32_bf16 v[118:121], v[146:149], v[198:201], v[118:121]
	v_mfma_f32_16x16x32_bf16 v[114:117], v[154:157], v[198:201], v[114:117]
	v_mfma_f32_16x16x32_bf16 v[102:105], v[146:149], v[206:209], v[102:105]
	v_mfma_f32_16x16x32_bf16 v[98:101], v[154:157], v[206:209], v[98:101]
	v_mfma_f32_16x16x32_bf16 v[86:89], v[146:149], v[214:217], v[86:89]
	v_mfma_f32_16x16x32_bf16 v[82:85], v[154:157], v[214:217], v[82:85]
	v_mfma_f32_16x16x32_bf16 v[134:137], v[150:153], v[166:169], v[134:137]
	v_mfma_f32_16x16x32_bf16 v[130:133], v[158:161], v[166:169], v[130:133]
	v_mfma_f32_16x16x32_bf16 v[118:121], v[150:153], v[202:205], v[118:121]
	v_mfma_f32_16x16x32_bf16 v[114:117], v[158:161], v[202:205], v[114:117]
	v_mfma_f32_16x16x32_bf16 v[102:105], v[150:153], v[210:213], v[102:105]
	v_mfma_f32_16x16x32_bf16 v[98:101], v[158:161], v[210:213], v[98:101]
	v_mfma_f32_16x16x32_bf16 v[86:89], v[150:153], v[218:221], v[86:89]
	v_mfma_f32_16x16x32_bf16 v[82:85], v[158:161], v[218:221], v[82:85]
	s_setprio 0
	s_barrier
	s_add_u32 s18, s72, 0x80
	s_addc_u32 s19, s73, 0
	s_add_i32 s93, s93, s25
	s_cmp_lg_u32 s100, 0
	s_cbranch_scc1 .Lh13_m1_r
	ds_read_b128 v[162:165], v223 offset:49152
	ds_read_b128 v[166:169], v223 offset:50176
	ds_read_b128 v[198:201], v223 offset:51200
	ds_read_b128 v[202:205], v223 offset:52224
	ds_read_b128 v[206:209], v223 offset:53248
	ds_read_b128 v[210:213], v223 offset:54272
	ds_read_b128 v[214:217], v223 offset:55296
	ds_read_b128 v[218:221], v223 offset:56320
.Lh13_m1_r:
	s_mov_b32 m0, s93
	v_lshl_add_u64 v[224:225], s[18:19], 0, v[194:195]
	global_load_lds_dwordx4 v[224:225], off
	s_add_i32 m0, s93, 0x2000
	v_lshl_add_u64 v[224:225], s[18:19], 0, v[170:171]
	s_add_u32 s18, s72, 0x40080
	s_addc_u32 s19, s73, 0
	s_add_i32 s72, s94, s25
	global_load_lds_dwordx4 v[224:225], off
	s_mov_b32 m0, s72
	v_lshl_add_u64 v[224:225], s[18:19], 0, v[194:195]
	global_load_lds_dwordx4 v[224:225], off
	v_lshl_add_u64 v[224:225], s[18:19], 0, v[170:171]
	s_add_i32 m0, s72, 0x2000
	s_nop 0
	global_load_lds_dwordx4 v[224:225], off
	s_mov_b32 m0, s82
	v_lshl_add_u64 v[224:225], s[26:27], 0, v[196:197]
	global_load_lds_dwordx4 v[224:225], off
	v_lshl_add_u64 v[224:225], s[26:27], 0, v[172:173]
	s_mov_b32 m0, s83
	s_nop 0
	global_load_lds_dwordx4 v[224:225], off
	s_waitcnt vmcnt(8)
	s_waitcnt lgkmcnt(0)
	s_barrier
	s_setprio 1
	s_waitcnt lgkmcnt(0)
	s_cmp_lg_u32 s100, 0
	s_cbranch_scc1 .Lh13_m1
	v_mfma_f32_16x16x32_bf16 v[62:65], v[66:69], v[162:165], v[62:65]
	v_mfma_f32_16x16x32_bf16 v[58:61], v[74:77], v[162:165], v[58:61]
	v_mfma_f32_16x16x32_bf16 v[46:49], v[66:69], v[198:201], v[46:49]
	v_mfma_f32_16x16x32_bf16 v[42:45], v[74:77], v[198:201], v[42:45]
	v_mfma_f32_16x16x32_bf16 v[30:33], v[66:69], v[206:209], v[30:33]
	v_mfma_f32_16x16x32_bf16 v[26:29], v[74:77], v[206:209], v[26:29]
	v_mfma_f32_16x16x32_bf16 v[14:17], v[66:69], v[214:217], v[14:17]
	v_mfma_f32_16x16x32_bf16 v[10:13], v[74:77], v[214:217], v[10:13]
	v_mfma_f32_16x16x32_bf16 v[62:65], v[70:73], v[166:169], v[62:65]
	v_mfma_f32_16x16x32_bf16 v[58:61], v[78:81], v[166:169], v[58:61]
	v_mfma_f32_16x16x32_bf16 v[46:49], v[70:73], v[202:205], v[46:49]
	v_mfma_f32_16x16x32_bf16 v[42:45], v[78:81], v[202:205], v[42:45]
	v_mfma_f32_16x16x32_bf16 v[30:33], v[70:73], v[210:213], v[30:33]
	v_mfma_f32_16x16x32_bf16 v[26:29], v[78:81], v[210:213], v[26:29]
	v_mfma_f32_16x16x32_bf16 v[14:17], v[70:73], v[218:221], v[14:17]
	v_mfma_f32_16x16x32_bf16 v[10:13], v[78:81], v[218:221], v[10:13]
	v_mfma_f32_16x16x32_bf16 v[54:57], v[146:149], v[162:165], v[54:57]
	v_mfma_f32_16x16x32_bf16 v[50:53], v[154:157], v[162:165], v[50:53]
	v_mfma_f32_16x16x32_bf16 v[38:41], v[146:149], v[198:201], v[38:41]
	v_mfma_f32_16x16x32_bf16 v[34:37], v[154:157], v[198:201], v[34:37]
	v_mfma_f32_16x16x32_bf16 v[22:25], v[146:149], v[206:209], v[22:25]
	v_mfma_f32_16x16x32_bf16 v[18:21], v[154:157], v[206:209], v[18:21]
	v_mfma_f32_16x16x32_bf16 v[6:9], v[146:149], v[214:217], v[6:9]
	v_mfma_f32_16x16x32_bf16 v[2:5], v[154:157], v[214:217], v[2:5]
	v_mfma_f32_16x16x32_bf16 v[54:57], v[150:153], v[166:169], v[54:57]
	v_mfma_f32_16x16x32_bf16 v[50:53], v[158:161], v[166:169], v[50:53]
	v_mfma_f32_16x16x32_bf16 v[38:41], v[150:153], v[202:205], v[38:41]
	v_mfma_f32_16x16x32_bf16 v[34:37], v[158:161], v[202:205], v[34:37]
	v_mfma_f32_16x16x32_bf16 v[22:25], v[150:153], v[210:213], v[22:25]
	v_mfma_f32_16x16x32_bf16 v[18:21], v[158:161], v[210:213], v[18:21]
	v_mfma_f32_16x16x32_bf16 v[6:9], v[150:153], v[218:221], v[6:9]
	v_mfma_f32_16x16x32_bf16 v[2:5], v[158:161], v[218:221], v[2:5]

.LBB0_1315:
	s_add_i32 s92, s18, 2
	s_cmp_eq_u32 s81, s18
	s_cselect_b32 s18, s37, vcc_lo
	s_cselect_b32 s19, s1, vcc_hi
	s_cselect_b32 s62, s89, s90
	s_cselect_b32 s63, s55, s91
	s_add_u32 s26, s18, 0x80
	s_addc_u32 s27, s19, 0
	s_add_i32 s93, 0, 0x10000
	v_add_u32_e32 v0, s93, v222
	s_add_i32 s96, 0, 0x14000
	ds_read_b128 v[66:69], v0
	ds_read_b128 v[70:73], v0 offset:1024
	ds_read_b128 v[74:77], v0 offset:2048
	ds_read_b128 v[78:81], v0 offset:3072
	v_add_u32_e32 v0, s96, v222
	ds_read_b128 v[146:149], v0
	ds_read_b128 v[150:153], v0 offset:1024
	ds_read_b128 v[154:157], v0 offset:2048
	ds_read_b128 v[158:161], v0 offset:3072
	s_mov_b64 s[2:3], s[94:95]
	ds_read_b128 v[162:165], v223
	ds_read_b128 v[166:169], v223 offset:1024
	ds_read_b128 v[198:201], v223 offset:2048
	ds_read_b128 v[202:205], v223 offset:3072
	ds_read_b128 v[206:209], v223 offset:4096
	ds_read_b128 v[210:213], v223 offset:5120
	ds_read_b128 v[214:217], v223 offset:6144
	ds_read_b128 v[218:221], v223 offset:7168
	s_add_i32 m0, s67, 0xc000
	v_lshl_add_u64 v[224:225], s[2:3], 0, v[196:197]
	global_load_lds_dwordx4 v[224:225], off
	v_lshl_add_u64 v[224:225], s[2:3], 0, v[172:173]
	s_add_i32 m0, s67, 0xe000
	s_nop 0
	global_load_lds_dwordx4 v[224:225], off
	s_waitcnt vmcnt(8)
	s_waitcnt lgkmcnt(0)
	s_barrier
	s_setprio 1
	s_waitcnt lgkmcnt(0)
	v_mfma_f32_16x16x32_bf16 v[138:141], v[66:69], v[162:165], v[138:141]
	v_mfma_f32_16x16x32_bf16 v[142:145], v[74:77], v[162:165], v[142:145]
	v_mfma_f32_16x16x32_bf16 v[126:129], v[66:69], v[198:201], v[126:129]
	v_mfma_f32_16x16x32_bf16 v[122:125], v[74:77], v[198:201], v[122:125]
	v_mfma_f32_16x16x32_bf16 v[110:113], v[66:69], v[206:209], v[110:113]
	v_mfma_f32_16x16x32_bf16 v[106:109], v[74:77], v[206:209], v[106:109]
	v_mfma_f32_16x16x32_bf16 v[94:97], v[66:69], v[214:217], v[94:97]
	v_mfma_f32_16x16x32_bf16 v[90:93], v[74:77], v[214:217], v[90:93]
	v_mfma_f32_16x16x32_bf16 v[138:141], v[70:73], v[166:169], v[138:141]
	v_mfma_f32_16x16x32_bf16 v[142:145], v[78:81], v[166:169], v[142:145]
	v_mfma_f32_16x16x32_bf16 v[126:129], v[70:73], v[202:205], v[126:129]
	v_mfma_f32_16x16x32_bf16 v[122:125], v[78:81], v[202:205], v[122:125]
	v_mfma_f32_16x16x32_bf16 v[110:113], v[70:73], v[210:213], v[110:113]
	v_mfma_f32_16x16x32_bf16 v[106:109], v[78:81], v[210:213], v[106:109]
	v_mfma_f32_16x16x32_bf16 v[94:97], v[70:73], v[218:221], v[94:97]
	v_mfma_f32_16x16x32_bf16 v[90:93], v[78:81], v[218:221], v[90:93]
	v_mfma_f32_16x16x32_bf16 v[134:137], v[146:149], v[162:165], v[134:137]
	v_mfma_f32_16x16x32_bf16 v[130:133], v[154:157], v[162:165], v[130:133]
	v_mfma_f32_16x16x32_bf16 v[118:121], v[146:149], v[198:201], v[118:121]
	v_mfma_f32_16x16x32_bf16 v[114:117], v[154:157], v[198:201], v[114:117]
	v_mfma_f32_16x16x32_bf16 v[102:105], v[146:149], v[206:209], v[102:105]
	v_mfma_f32_16x16x32_bf16 v[98:101], v[154:157], v[206:209], v[98:101]
	v_mfma_f32_16x16x32_bf16 v[86:89], v[146:149], v[214:217], v[86:89]
	v_mfma_f32_16x16x32_bf16 v[82:85], v[154:157], v[214:217], v[82:85]
	v_mfma_f32_16x16x32_bf16 v[134:137], v[150:153], v[166:169], v[134:137]
	v_mfma_f32_16x16x32_bf16 v[130:133], v[158:161], v[166:169], v[130:133]
	v_mfma_f32_16x16x32_bf16 v[118:121], v[150:153], v[202:205], v[118:121]
	v_mfma_f32_16x16x32_bf16 v[114:117], v[158:161], v[202:205], v[114:117]
	v_mfma_f32_16x16x32_bf16 v[102:105], v[150:153], v[210:213], v[102:105]
	v_mfma_f32_16x16x32_bf16 v[98:101], v[158:161], v[210:213], v[98:101]
	v_mfma_f32_16x16x32_bf16 v[86:89], v[150:153], v[218:221], v[86:89]
	v_mfma_f32_16x16x32_bf16 v[82:85], v[158:161], v[218:221], v[82:85]
	s_setprio 0
	s_barrier
	s_mov_b64 s[2:3], s[62:63]
	s_add_i32 s93, s93, s25
	s_cmp_lg_u32 s100, 0
	s_cbranch_scc1 .Lh8_m0_r
	ds_read_b128 v[162:165], v223 offset:16384
	ds_read_b128 v[166:169], v223 offset:17408
	ds_read_b128 v[198:201], v223 offset:18432
	ds_read_b128 v[202:205], v223 offset:19456
	ds_read_b128 v[206:209], v223 offset:20480
	ds_read_b128 v[210:213], v223 offset:21504
	ds_read_b128 v[214:217], v223 offset:22528
	ds_read_b128 v[218:221], v223 offset:23552
.Lh8_m0_r:
	s_mov_b32 m0, s93
	v_lshl_add_u64 v[224:225], s[2:3], 0, v[194:195]
	global_load_lds_dwordx4 v[224:225], off
	s_add_i32 m0, s93, 0x2000
	v_lshl_add_u64 v[224:225], s[2:3], 0, v[170:171]
	s_add_u32 s2, s62, 0x40000
	s_addc_u32 s3, s63, 0
	s_add_i32 s93, s96, s25
	global_load_lds_dwordx4 v[224:225], off
	s_mov_b32 m0, s93
	v_lshl_add_u64 v[224:225], s[2:3], 0, v[194:195]
	global_load_lds_dwordx4 v[224:225], off
	v_lshl_add_u64 v[224:225], s[2:3], 0, v[170:171]
	s_add_i32 m0, s93, 0x2000
	s_mov_b64 s[2:3], s[18:19]
	global_load_lds_dwordx4 v[224:225], off
	s_mov_b32 m0, s67
	v_lshl_add_u64 v[224:225], s[2:3], 0, v[196:197]
	global_load_lds_dwordx4 v[224:225], off
	v_lshl_add_u64 v[224:225], s[2:3], 0, v[172:173]
	s_mov_b32 m0, s68
	s_nop 0
	global_load_lds_dwordx4 v[224:225], off
	s_waitcnt vmcnt(8)
	s_waitcnt lgkmcnt(0)
	s_barrier
	s_setprio 1
	s_waitcnt lgkmcnt(0)
	s_cmp_lg_u32 s100, 0
	s_cbranch_scc1 .Lh8_m0
	v_mfma_f32_16x16x32_bf16 v[62:65], v[66:69], v[162:165], v[62:65]
	v_mfma_f32_16x16x32_bf16 v[58:61], v[74:77], v[162:165], v[58:61]
	v_mfma_f32_16x16x32_bf16 v[46:49], v[66:69], v[198:201], v[46:49]
	v_mfma_f32_16x16x32_bf16 v[42:45], v[74:77], v[198:201], v[42:45]
	v_mfma_f32_16x16x32_bf16 v[30:33], v[66:69], v[206:209], v[30:33]
	v_mfma_f32_16x16x32_bf16 v[26:29], v[74:77], v[206:209], v[26:29]
	v_mfma_f32_16x16x32_bf16 v[14:17], v[66:69], v[214:217], v[14:17]
	v_mfma_f32_16x16x32_bf16 v[10:13], v[74:77], v[214:217], v[10:13]
	v_mfma_f32_16x16x32_bf16 v[62:65], v[70:73], v[166:169], v[62:65]
	v_mfma_f32_16x16x32_bf16 v[58:61], v[78:81], v[166:169], v[58:61]
	v_mfma_f32_16x16x32_bf16 v[46:49], v[70:73], v[202:205], v[46:49]
	v_mfma_f32_16x16x32_bf16 v[42:45], v[78:81], v[202:205], v[42:45]
	v_mfma_f32_16x16x32_bf16 v[30:33], v[70:73], v[210:213], v[30:33]
	v_mfma_f32_16x16x32_bf16 v[26:29], v[78:81], v[210:213], v[26:29]
	v_mfma_f32_16x16x32_bf16 v[14:17], v[70:73], v[218:221], v[14:17]
	v_mfma_f32_16x16x32_bf16 v[10:13], v[78:81], v[218:221], v[10:13]
	v_mfma_f32_16x16x32_bf16 v[54:57], v[146:149], v[162:165], v[54:57]
	v_mfma_f32_16x16x32_bf16 v[50:53], v[154:157], v[162:165], v[50:53]
	v_mfma_f32_16x16x32_bf16 v[38:41], v[146:149], v[198:201], v[38:41]
	v_mfma_f32_16x16x32_bf16 v[34:37], v[154:157], v[198:201], v[34:37]
	v_mfma_f32_16x16x32_bf16 v[22:25], v[146:149], v[206:209], v[22:25]
	v_mfma_f32_16x16x32_bf16 v[18:21], v[154:157], v[206:209], v[18:21]
	v_mfma_f32_16x16x32_bf16 v[6:9], v[146:149], v[214:217], v[6:9]
	v_mfma_f32_16x16x32_bf16 v[2:5], v[154:157], v[214:217], v[2:5]
	v_mfma_f32_16x16x32_bf16 v[54:57], v[150:153], v[166:169], v[54:57]
	v_mfma_f32_16x16x32_bf16 v[50:53], v[158:161], v[166:169], v[50:53]
	v_mfma_f32_16x16x32_bf16 v[38:41], v[150:153], v[202:205], v[38:41]
	v_mfma_f32_16x16x32_bf16 v[34:37], v[158:161], v[202:205], v[34:37]
	v_mfma_f32_16x16x32_bf16 v[22:25], v[150:153], v[210:213], v[22:25]
	v_mfma_f32_16x16x32_bf16 v[18:21], v[158:161], v[210:213], v[18:21]
	v_mfma_f32_16x16x32_bf16 v[6:9], v[150:153], v[218:221], v[6:9]
	v_mfma_f32_16x16x32_bf16 v[2:5], v[158:161], v[218:221], v[2:5]
.Lh8_m0:
	s_setprio 0
	s_barrier
	s_add_i32 s93, 0, 0x18000
	v_add_u32_e32 v0, s93, v222
	s_add_i32 s96, 0, 0x1c000
	ds_read_b128 v[66:69], v0
	ds_read_b128 v[70:73], v0 offset:1024
	ds_read_b128 v[74:77], v0 offset:2048
	ds_read_b128 v[78:81], v0 offset:3072
	v_add_u32_e32 v0, s96, v222
	ds_read_b128 v[146:149], v0
	ds_read_b128 v[150:153], v0 offset:1024
	ds_read_b128 v[154:157], v0 offset:2048
	ds_read_b128 v[158:161], v0 offset:3072
	s_add_u32 s2, s18, 0x40000
	s_addc_u32 s3, s19, 0
	s_mov_b32 m0, s69
	ds_read_b128 v[162:165], v223 offset:32768
	ds_read_b128 v[166:169], v223 offset:33792
	ds_read_b128 v[198:201], v223 offset:34816
	ds_read_b128 v[202:205], v223 offset:35840
	ds_read_b128 v[206:209], v223 offset:36864
	ds_read_b128 v[210:213], v223 offset:37888
	ds_read_b128 v[214:217], v223 offset:38912
	ds_read_b128 v[218:221], v223 offset:39936
	s_nop 0
	v_lshl_add_u64 v[224:225], s[2:3], 0, v[196:197]
	global_load_lds_dwordx4 v[224:225], off
	v_lshl_add_u64 v[224:225], s[2:3], 0, v[172:173]
	s_mov_b32 m0, s70
	s_nop 0
	global_load_lds_dwordx4 v[224:225], off
	s_waitcnt vmcnt(8)
	s_waitcnt lgkmcnt(0)
	s_barrier
	s_setprio 1
	s_waitcnt lgkmcnt(0)
	v_mfma_f32_16x16x32_bf16 v[138:141], v[66:69], v[162:165], v[138:141]
	v_mfma_f32_16x16x32_bf16 v[142:145], v[74:77], v[162:165], v[142:145]
	v_mfma_f32_16x16x32_bf16 v[126:129], v[66:69], v[198:201], v[126:129]
	v_mfma_f32_16x16x32_bf16 v[122:125], v[74:77], v[198:201], v[122:125]
	v_mfma_f32_16x16x32_bf16 v[110:113], v[66:69], v[206:209], v[110:113]
	v_mfma_f32_16x16x32_bf16 v[106:109], v[74:77], v[206:209], v[106:109]
	v_mfma_f32_16x16x32_bf16 v[94:97], v[66:69], v[214:217], v[94:97]
	v_mfma_f32_16x16x32_bf16 v[90:93], v[74:77], v[214:217], v[90:93]
	v_mfma_f32_16x16x32_bf16 v[138:141], v[70:73], v[166:169], v[138:141]
	v_mfma_f32_16x16x32_bf16 v[142:145], v[78:81], v[166:169], v[142:145]
	v_mfma_f32_16x16x32_bf16 v[126:129], v[70:73], v[202:205], v[126:129]
	v_mfma_f32_16x16x32_bf16 v[122:125], v[78:81], v[202:205], v[122:125]
	v_mfma_f32_16x16x32_bf16 v[110:113], v[70:73], v[210:213], v[110:113]
	v_mfma_f32_16x16x32_bf16 v[106:109], v[78:81], v[210:213], v[106:109]
	v_mfma_f32_16x16x32_bf16 v[94:97], v[70:73], v[218:221], v[94:97]
	v_mfma_f32_16x16x32_bf16 v[90:93], v[78:81], v[218:221], v[90:93]
	v_mfma_f32_16x16x32_bf16 v[134:137], v[146:149], v[162:165], v[134:137]
	v_mfma_f32_16x16x32_bf16 v[130:133], v[154:157], v[162:165], v[130:133]
	v_mfma_f32_16x16x32_bf16 v[118:121], v[146:149], v[198:201], v[118:121]
	v_mfma_f32_16x16x32_bf16 v[114:117], v[154:157], v[198:201], v[114:117]
	v_mfma_f32_16x16x32_bf16 v[102:105], v[146:149], v[206:209], v[102:105]
	v_mfma_f32_16x16x32_bf16 v[98:101], v[154:157], v[206:209], v[98:101]
	v_mfma_f32_16x16x32_bf16 v[86:89], v[146:149], v[214:217], v[86:89]
	v_mfma_f32_16x16x32_bf16 v[82:85], v[154:157], v[214:217], v[82:85]
	v_mfma_f32_16x16x32_bf16 v[134:137], v[150:153], v[166:169], v[134:137]
	v_mfma_f32_16x16x32_bf16 v[130:133], v[158:161], v[166:169], v[130:133]
	v_mfma_f32_16x16x32_bf16 v[118:121], v[150:153], v[202:205], v[118:121]
	v_mfma_f32_16x16x32_bf16 v[114:117], v[158:161], v[202:205], v[114:117]
	v_mfma_f32_16x16x32_bf16 v[102:105], v[150:153], v[210:213], v[102:105]
	v_mfma_f32_16x16x32_bf16 v[98:101], v[158:161], v[210:213], v[98:101]
	v_mfma_f32_16x16x32_bf16 v[86:89], v[150:153], v[218:221], v[86:89]
	v_mfma_f32_16x16x32_bf16 v[82:85], v[158:161], v[218:221], v[82:85]
	s_setprio 0
	s_barrier
	s_add_u32 s2, s62, 0x80
	s_addc_u32 s3, s63, 0
	s_add_i32 s18, s93, s25
	s_cmp_lg_u32 s100, 0
	s_cbranch_scc1 .Lh8_m1_r
	ds_read_b128 v[162:165], v223 offset:49152
	ds_read_b128 v[166:169], v223 offset:50176
	ds_read_b128 v[198:201], v223 offset:51200
	ds_read_b128 v[202:205], v223 offset:52224
	ds_read_b128 v[206:209], v223 offset:53248
	ds_read_b128 v[210:213], v223 offset:54272
	ds_read_b128 v[214:217], v223 offset:55296
	ds_read_b128 v[218:221], v223 offset:56320
.Lh8_m1_r:
	s_mov_b32 m0, s18
	v_lshl_add_u64 v[224:225], s[2:3], 0, v[194:195]
	global_load_lds_dwordx4 v[224:225], off
	s_add_i32 m0, s18, 0x2000
	v_lshl_add_u64 v[224:225], s[2:3], 0, v[170:171]
	s_add_u32 s2, s62, 0x40080
	s_addc_u32 s3, s63, 0
	s_add_i32 s18, s96, s25
	global_load_lds_dwordx4 v[224:225], off
	s_mov_b32 m0, s18
	v_lshl_add_u64 v[224:225], s[2:3], 0, v[194:195]
	global_load_lds_dwordx4 v[224:225], off
	v_lshl_add_u64 v[224:225], s[2:3], 0, v[170:171]
	s_add_i32 m0, s18, 0x2000
	s_nop 0
	global_load_lds_dwordx4 v[224:225], off
	s_mov_b32 m0, s82
	v_lshl_add_u64 v[224:225], s[26:27], 0, v[196:197]
	global_load_lds_dwordx4 v[224:225], off
	v_lshl_add_u64 v[224:225], s[26:27], 0, v[172:173]
	s_mov_b32 m0, s83
	s_nop 0
	global_load_lds_dwordx4 v[224:225], off
	s_waitcnt vmcnt(8)
	s_waitcnt lgkmcnt(0)
	s_barrier
	s_setprio 1
	s_waitcnt lgkmcnt(0)
	s_cmp_lg_u32 s100, 0
	s_cbranch_scc1 .Lh8_m1
	v_mfma_f32_16x16x32_bf16 v[62:65], v[66:69], v[162:165], v[62:65]
	v_mfma_f32_16x16x32_bf16 v[58:61], v[74:77], v[162:165], v[58:61]
	v_mfma_f32_16x16x32_bf16 v[46:49], v[66:69], v[198:201], v[46:49]
	v_mfma_f32_16x16x32_bf16 v[42:45], v[74:77], v[198:201], v[42:45]
	v_mfma_f32_16x16x32_bf16 v[30:33], v[66:69], v[206:209], v[30:33]
	v_mfma_f32_16x16x32_bf16 v[26:29], v[74:77], v[206:209], v[26:29]
	v_mfma_f32_16x16x32_bf16 v[14:17], v[66:69], v[214:217], v[14:17]
	v_mfma_f32_16x16x32_bf16 v[10:13], v[74:77], v[214:217], v[10:13]
	v_mfma_f32_16x16x32_bf16 v[62:65], v[70:73], v[166:169], v[62:65]
	v_mfma_f32_16x16x32_bf16 v[58:61], v[78:81], v[166:169], v[58:61]
	v_mfma_f32_16x16x32_bf16 v[46:49], v[70:73], v[202:205], v[46:49]
	v_mfma_f32_16x16x32_bf16 v[42:45], v[78:81], v[202:205], v[42:45]
	v_mfma_f32_16x16x32_bf16 v[30:33], v[70:73], v[210:213], v[30:33]
	v_mfma_f32_16x16x32_bf16 v[26:29], v[78:81], v[210:213], v[26:29]
	v_mfma_f32_16x16x32_bf16 v[14:17], v[70:73], v[218:221], v[14:17]
	v_mfma_f32_16x16x32_bf16 v[10:13], v[78:81], v[218:221], v[10:13]
	v_mfma_f32_16x16x32_bf16 v[54:57], v[146:149], v[162:165], v[54:57]
	v_mfma_f32_16x16x32_bf16 v[50:53], v[154:157], v[162:165], v[50:53]
	v_mfma_f32_16x16x32_bf16 v[38:41], v[146:149], v[198:201], v[38:41]
	v_mfma_f32_16x16x32_bf16 v[34:37], v[154:157], v[198:201], v[34:37]
	v_mfma_f32_16x16x32_bf16 v[22:25], v[146:149], v[206:209], v[22:25]
	v_mfma_f32_16x16x32_bf16 v[18:21], v[154:157], v[206:209], v[18:21]
	v_mfma_f32_16x16x32_bf16 v[6:9], v[146:149], v[214:217], v[6:9]
	v_mfma_f32_16x16x32_bf16 v[2:5], v[154:157], v[214:217], v[2:5]
	v_mfma_f32_16x16x32_bf16 v[54:57], v[150:153], v[166:169], v[54:57]
	v_mfma_f32_16x16x32_bf16 v[50:53], v[158:161], v[166:169], v[50:53]
	v_mfma_f32_16x16x32_bf16 v[38:41], v[150:153], v[202:205], v[38:41]
	v_mfma_f32_16x16x32_bf16 v[34:37], v[158:161], v[202:205], v[34:37]
	v_mfma_f32_16x16x32_bf16 v[22:25], v[150:153], v[210:213], v[22:25]
	v_mfma_f32_16x16x32_bf16 v[18:21], v[158:161], v[210:213], v[18:21]
	v_mfma_f32_16x16x32_bf16 v[6:9], v[150:153], v[218:221], v[6:9]
	v_mfma_f32_16x16x32_bf16 v[2:5], v[158:161], v[218:221], v[2:5]
